# baseline (speedup 1.0000x reference)
; __device__ __forceinline__ unsigned cvt_pk_bf16(float lo, float hi) { unsigned r; asm volatile("v_cvt_pk_bf16_f32 %0, %1, %2" : "=v"(r) : "v"(lo), "v"(hi)); return r; }
;     __device__ __forceinline__ void fused(f32x4 (&acc)[2][2][4][2], const Unit& u, int wr, int wc, int fr, int fq, LAS unsigned char* lds) const {
;     ...
;         asm volatile("s_waitcnt lgkmcnt(0)" ::: "memory"); __builtin_amdgcn_s_barrier(); asm volatile("" ::: "memory");
; #pragma unroll
;         for (int bj = 0; bj < 2; ++bj)
; #pragma unroll
;             for (int n = 0; n < 2; ++n) { const int cc = col0 + bj * HALF + n * 16; const f32x4 g4 = *(const f32x4*)(g + cc), b4 = *(const f32x4*)(b + cc);
; #pragma unroll
;                 for (int ai = 0; ai < 2; ++ai)
; #pragma unroll
;                     for (int m = 0; m < 4; ++m) { const int rl = rl0 + ai * HALF + m * 16; const float mean = S2[rl * 2], rstd = S2[rl * 2 + 1];
;                         const f32x4 y = (acc[ai][bj][m][n] - mean) * rstd * g4 + b4; const size_t row = (size_t)(u.pm * BM + rl);
;                         if (of) *(f32x4*)(of + row * DM + cc) = y;
;                         else { u32x2 pk; pk.x = cvt_pk_bf16(y[0], y[1]); pk.y = cvt_pk_bf16(y[2], y[3]); *(u32x2*)(ob + row * LDX + cc) = pk; } }
;                 asm volatile("" ::: "memory"); }
.LBB0_579:
	s_or_b64 exec, exec, s[10:11]
	v_readlane_b32 s0, v253, 4
	v_lshlrev_b64 v[4:5], 2, v[134:135]
	v_readlane_b32 s1, v253, 5
	s_waitcnt lgkmcnt(0)
	s_barrier
	ds_read_b64 v[208:209], v238
	ds_read_b64 v[210:211], v239
	ds_read_b64 v[212:213], v240
	ds_read_b64 v[214:215], v241
	ds_read_b64 v[246:247], v242
	ds_read_b32 v181, v243
	ds_read_b32 v161, v243 offset:4
	ds_read_b32 v183, v244
	ds_read_b32 v167, v244 offset:4
	ds_read_b32 v64, v245
	ds_read_b32 v169, v245 offset:4
	v_lshl_add_u64 v[176:177], s[0:1], 0, v[4:5]
	v_readlane_b32 s0, v253, 2
	v_readlane_b32 s1, v253, 3
	s_waitcnt lgkmcnt(1)
	global_load_dwordx4 v[0:3], v[176:177], off
	s_waitcnt lgkmcnt(0)
	v_sub_f32_e32 v11, v120, v208
	v_lshl_add_u64 v[178:179], s[0:1], 0, v[4:5]
	global_load_dwordx4 v[4:7], v[178:179], off
	v_sub_f32_e32 v10, v118, v208
	v_sub_f32_e32 v121, v140, v208
	v_sub_f32_e32 v120, v124, v208
	v_readlane_b32 s2, v253, 10
	v_pk_mul_f32 v[120:121], v[120:121], v[208:209] op_sel:[0,1]
	v_pk_mul_f32 v[8:9], v[10:11], v[208:209] op_sel:[0,1]
	v_readlane_b32 s3, v253, 11
	s_andn2_b64 vcc, exec, s[2:3]
	s_waitcnt vmcnt(0)
	v_pk_fma_f32 v[10:11], v[2:3], v[8:9], v[6:7]
	v_pk_fma_f32 v[8:9], v[0:1], v[120:121], v[4:5]
	v_cndmask_b32_e64 v39, 0, 1, s[2:3]
	v_lshlrev_b64 v[120:121], 13, v[138:139]
	v_cmp_ne_u32_e64 s[0:1], 1, v39
	v_lshl_add_u64 v[138:139], s[14:15], 0, v[120:121]
	s_cbranch_vccnz .LBB0_677
	v_lshl_add_u64 v[120:121], v[134:135], 2, v[138:139]
	global_store_dwordx4 v[120:121], v[8:11], off
	v_lshl_add_u64 v[120:121], s[22:23], 0, v[198:199]
	v_lshl_add_u64 v[120:121], v[134:135], 1, v[120:121]
	s_cbranch_execnz .LBB0_582

; __device__ __forceinline__ unsigned cvt_pk_bf16(float lo, float hi) { unsigned r; asm volatile("v_cvt_pk_bf16_f32 %0, %1, %2" : "=v"(r) : "v"(lo), "v"(hi)); return r; }
;     __device__ __forceinline__ void fused(f32x4 (&acc)[2][2][4][2], const Unit& u, int wr, int wc, int fr, int fq, LAS unsigned char* lds) const {
;     ...
; #pragma unroll
;         for (int bj = 0; bj < 2; ++bj)
; #pragma unroll
;             for (int n = 0; n < 2; ++n) { const int cc = col0 + bj * HALF + n * 16; const f32x4 g4 = *(const f32x4*)(g + cc), b4 = *(const f32x4*)(b + cc);
; #pragma unroll
;                 for (int ai = 0; ai < 2; ++ai)
; #pragma unroll
;                     for (int m = 0; m < 4; ++m) { const int rl = rl0 + ai * HALF + m * 16; const float mean = S2[rl * 2], rstd = S2[rl * 2 + 1];
;                         const f32x4 y = (acc[ai][bj][m][n] - mean) * rstd * g4 + b4; const size_t row = (size_t)(u.pm * BM + rl);
;                         if (of) *(f32x4*)(of + row * DM + cc) = y;
;                         else { u32x2 pk; pk.x = cvt_pk_bf16(y[0], y[1]); pk.y = cvt_pk_bf16(y[2], y[3]); *(u32x2*)(ob + row * LDX + cc) = pk; } }
;                 asm volatile("" ::: "memory"); }
.LBB0_582:
	s_and_b64 vcc, exec, s[0:1]
	s_waitcnt lgkmcnt(0)
	v_sub_f32_e32 v11, v104, v210
	v_sub_f32_e32 v10, v102, v210
	v_sub_f32_e32 v105, v144, v210
	v_sub_f32_e32 v104, v108, v210
	v_pk_mul_f32 v[104:105], v[104:105], v[210:211] op_sel:[0,1]
	v_pk_mul_f32 v[8:9], v[10:11], v[210:211] op_sel:[0,1]
	s_nop 0
	v_pk_fma_f32 v[10:11], v[2:3], v[8:9], v[6:7]
	v_pk_fma_f32 v[8:9], v[0:1], v[104:105], v[4:5]
	v_lshlrev_b64 v[104:105], 13, v[142:143]
	v_lshl_add_u64 v[140:141], s[14:15], 0, v[104:105]
	s_cbranch_vccnz .LBB0_678
	v_lshl_add_u64 v[104:105], v[134:135], 2, v[140:141]
	global_store_dwordx4 v[104:105], v[8:11], off
	v_lshl_add_u64 v[104:105], s[22:23], 0, v[196:197]
	v_lshl_add_u64 v[104:105], v[134:135], 1, v[104:105]
	s_cbranch_execnz .LBB0_585

; __device__ __forceinline__ unsigned cvt_pk_bf16(float lo, float hi) { unsigned r; asm volatile("v_cvt_pk_bf16_f32 %0, %1, %2" : "=v"(r) : "v"(lo), "v"(hi)); return r; }
;     __device__ __forceinline__ void fused(f32x4 (&acc)[2][2][4][2], const Unit& u, int wr, int wc, int fr, int fq, LAS unsigned char* lds) const {
;     ...
; #pragma unroll
;         for (int bj = 0; bj < 2; ++bj)
; #pragma unroll
;             for (int n = 0; n < 2; ++n) { const int cc = col0 + bj * HALF + n * 16; const f32x4 g4 = *(const f32x4*)(g + cc), b4 = *(const f32x4*)(b + cc);
; #pragma unroll
;                 for (int ai = 0; ai < 2; ++ai)
; #pragma unroll
;                     for (int m = 0; m < 4; ++m) { const int rl = rl0 + ai * HALF + m * 16; const float mean = S2[rl * 2], rstd = S2[rl * 2 + 1];
;                         const f32x4 y = (acc[ai][bj][m][n] - mean) * rstd * g4 + b4; const size_t row = (size_t)(u.pm * BM + rl);
;                         if (of) *(f32x4*)(of + row * DM + cc) = y;
;                         else { u32x2 pk; pk.x = cvt_pk_bf16(y[0], y[1]); pk.y = cvt_pk_bf16(y[2], y[3]); *(u32x2*)(ob + row * LDX + cc) = pk; } }
;                 asm volatile("" ::: "memory"); }
.LBB0_585:
	s_and_b64 vcc, exec, s[0:1]
	s_waitcnt lgkmcnt(0)
	v_sub_f32_e32 v11, v88, v212
	v_sub_f32_e32 v10, v86, v212
	v_sub_f32_e32 v89, v148, v212
	v_sub_f32_e32 v88, v92, v212
	v_pk_mul_f32 v[88:89], v[88:89], v[212:213] op_sel:[0,1]
	v_pk_mul_f32 v[8:9], v[10:11], v[212:213] op_sel:[0,1]
	s_nop 0
	v_pk_fma_f32 v[10:11], v[2:3], v[8:9], v[6:7]
	v_pk_fma_f32 v[8:9], v[0:1], v[88:89], v[4:5]
	v_lshlrev_b64 v[88:89], 13, v[146:147]
	v_lshl_add_u64 v[142:143], s[14:15], 0, v[88:89]
	s_cbranch_vccnz .LBB0_679
	v_lshl_add_u64 v[88:89], v[134:135], 2, v[142:143]
	global_store_dwordx4 v[88:89], v[8:11], off
	v_lshl_add_u64 v[88:89], s[22:23], 0, v[194:195]
	v_lshl_add_u64 v[88:89], v[134:135], 1, v[88:89]
	s_cbranch_execnz .LBB0_588

; __device__ __forceinline__ unsigned cvt_pk_bf16(float lo, float hi) { unsigned r; asm volatile("v_cvt_pk_bf16_f32 %0, %1, %2" : "=v"(r) : "v"(lo), "v"(hi)); return r; }
;     __device__ __forceinline__ void fused(f32x4 (&acc)[2][2][4][2], const Unit& u, int wr, int wc, int fr, int fq, LAS unsigned char* lds) const {
;     ...
; #pragma unroll
;         for (int bj = 0; bj < 2; ++bj)
; #pragma unroll
;             for (int n = 0; n < 2; ++n) { const int cc = col0 + bj * HALF + n * 16; const f32x4 g4 = *(const f32x4*)(g + cc), b4 = *(const f32x4*)(b + cc);
; #pragma unroll
;                 for (int ai = 0; ai < 2; ++ai)
; #pragma unroll
;                     for (int m = 0; m < 4; ++m) { const int rl = rl0 + ai * HALF + m * 16; const float mean = S2[rl * 2], rstd = S2[rl * 2 + 1];
;                         const f32x4 y = (acc[ai][bj][m][n] - mean) * rstd * g4 + b4; const size_t row = (size_t)(u.pm * BM + rl);
;                         if (of) *(f32x4*)(of + row * DM + cc) = y;
;                         else { u32x2 pk; pk.x = cvt_pk_bf16(y[0], y[1]); pk.y = cvt_pk_bf16(y[2], y[3]); *(u32x2*)(ob + row * LDX + cc) = pk; } }
;                 asm volatile("" ::: "memory"); }
.LBB0_588:
	s_and_b64 vcc, exec, s[0:1]
	s_waitcnt lgkmcnt(0)
	v_sub_f32_e32 v11, v72, v214
	v_sub_f32_e32 v10, v70, v214
	v_sub_f32_e32 v73, v152, v214
	v_sub_f32_e32 v72, v76, v214
	v_pk_mul_f32 v[72:73], v[72:73], v[214:215] op_sel:[0,1]
	v_pk_mul_f32 v[8:9], v[10:11], v[214:215] op_sel:[0,1]
	s_nop 0
	v_pk_fma_f32 v[10:11], v[2:3], v[8:9], v[6:7]
	v_pk_fma_f32 v[8:9], v[0:1], v[72:73], v[4:5]
	v_lshlrev_b64 v[72:73], 13, v[150:151]
	v_lshl_add_u64 v[144:145], s[14:15], 0, v[72:73]
	s_cbranch_vccnz .LBB0_680
	v_lshl_add_u64 v[72:73], v[134:135], 2, v[144:145]
	global_store_dwordx4 v[72:73], v[8:11], off
	v_lshl_add_u64 v[72:73], s[22:23], 0, v[192:193]
	v_lshl_add_u64 v[72:73], v[134:135], 1, v[72:73]
	s_cbranch_execnz .LBB0_591

; __device__ __forceinline__ unsigned cvt_pk_bf16(float lo, float hi) { unsigned r; asm volatile("v_cvt_pk_bf16_f32 %0, %1, %2" : "=v"(r) : "v"(lo), "v"(hi)); return r; }
;     __device__ __forceinline__ void fused(f32x4 (&acc)[2][2][4][2], const Unit& u, int wr, int wc, int fr, int fq, LAS unsigned char* lds) const {
;     ...
; #pragma unroll
;         for (int bj = 0; bj < 2; ++bj)
; #pragma unroll
;             for (int n = 0; n < 2; ++n) { const int cc = col0 + bj * HALF + n * 16; const f32x4 g4 = *(const f32x4*)(g + cc), b4 = *(const f32x4*)(b + cc);
; #pragma unroll
;                 for (int ai = 0; ai < 2; ++ai)
; #pragma unroll
;                     for (int m = 0; m < 4; ++m) { const int rl = rl0 + ai * HALF + m * 16; const float mean = S2[rl * 2], rstd = S2[rl * 2 + 1];
;                         const f32x4 y = (acc[ai][bj][m][n] - mean) * rstd * g4 + b4; const size_t row = (size_t)(u.pm * BM + rl);
;                         if (of) *(f32x4*)(of + row * DM + cc) = y;
;                         else { u32x2 pk; pk.x = cvt_pk_bf16(y[0], y[1]); pk.y = cvt_pk_bf16(y[2], y[3]); *(u32x2*)(ob + row * LDX + cc) = pk; } }
;                 asm volatile("" ::: "memory"); }
.LBB0_591:
	s_and_b64 vcc, exec, s[0:1]
	s_waitcnt lgkmcnt(0)
	v_sub_f32_e32 v11, v54, v246
	v_sub_f32_e32 v10, v52, v246
	v_sub_f32_e32 v55, v156, v246
	v_sub_f32_e32 v54, v58, v246
	v_pk_mul_f32 v[54:55], v[54:55], v[246:247] op_sel:[0,1]
	v_pk_mul_f32 v[8:9], v[10:11], v[246:247] op_sel:[0,1]
	s_nop 0
	v_pk_fma_f32 v[10:11], v[2:3], v[8:9], v[6:7]
	v_pk_fma_f32 v[8:9], v[0:1], v[54:55], v[4:5]
	v_lshlrev_b64 v[54:55], 13, v[154:155]
	v_lshl_add_u64 v[148:149], s[14:15], 0, v[54:55]
	s_cbranch_vccnz .LBB0_681
	v_lshl_add_u64 v[54:55], v[134:135], 2, v[148:149]
	global_store_dwordx4 v[54:55], v[8:11], off
	v_lshl_add_u64 v[54:55], s[22:23], 0, v[190:191]
	v_lshl_add_u64 v[54:55], v[134:135], 1, v[54:55]
	s_cbranch_execnz .LBB0_594

; __device__ __forceinline__ unsigned cvt_pk_bf16(float lo, float hi) { unsigned r; asm volatile("v_cvt_pk_bf16_f32 %0, %1, %2" : "=v"(r) : "v"(lo), "v"(hi)); return r; }
;     __device__ __forceinline__ void fused(f32x4 (&acc)[2][2][4][2], const Unit& u, int wr, int wc, int fr, int fq, LAS unsigned char* lds) const {
;     ...
; #pragma unroll
;         for (int bj = 0; bj < 2; ++bj)
; #pragma unroll
;             for (int n = 0; n < 2; ++n) { const int cc = col0 + bj * HALF + n * 16; const f32x4 g4 = *(const f32x4*)(g + cc), b4 = *(const f32x4*)(b + cc);
; #pragma unroll
;                 for (int ai = 0; ai < 2; ++ai)
; #pragma unroll
;                     for (int m = 0; m < 4; ++m) { const int rl = rl0 + ai * HALF + m * 16; const float mean = S2[rl * 2], rstd = S2[rl * 2 + 1];
;                         const f32x4 y = (acc[ai][bj][m][n] - mean) * rstd * g4 + b4; const size_t row = (size_t)(u.pm * BM + rl);
;                         if (of) *(f32x4*)(of + row * DM + cc) = y;
;                         else { u32x2 pk; pk.x = cvt_pk_bf16(y[0], y[1]); pk.y = cvt_pk_bf16(y[2], y[3]); *(u32x2*)(ob + row * LDX + cc) = pk; } }
;                 asm volatile("" ::: "memory"); }
.LBB0_594:
	s_and_b64 vcc, exec, s[0:1]
	s_waitcnt lgkmcnt(0)
	v_sub_f32_e32 v11, v38, v181
	v_sub_f32_e32 v10, v36, v181
	v_sub_f32_e32 v39, v160, v181
	v_sub_f32_e32 v38, v42, v181
	v_pk_mul_f32 v[38:39], v[38:39], v[160:161] op_sel:[0,1]
	v_pk_mul_f32 v[8:9], v[10:11], v[160:161] op_sel:[0,1]
	s_nop 0
	v_pk_fma_f32 v[10:11], v[2:3], v[8:9], v[6:7]
	v_pk_fma_f32 v[8:9], v[0:1], v[38:39], v[4:5]
	v_lshlrev_b64 v[38:39], 13, v[158:159]
	v_lshl_add_u64 v[152:153], s[14:15], 0, v[38:39]
	s_cbranch_vccnz .LBB0_682
	v_lshl_add_u64 v[38:39], v[134:135], 2, v[152:153]
	global_store_dwordx4 v[38:39], v[8:11], off
	v_lshl_add_u64 v[38:39], s[22:23], 0, v[188:189]
	v_lshl_add_u64 v[38:39], v[134:135], 1, v[38:39]
	s_cbranch_execnz .LBB0_597

; __device__ __forceinline__ unsigned cvt_pk_bf16(float lo, float hi) { unsigned r; asm volatile("v_cvt_pk_bf16_f32 %0, %1, %2" : "=v"(r) : "v"(lo), "v"(hi)); return r; }
;     __device__ __forceinline__ void fused(f32x4 (&acc)[2][2][4][2], const Unit& u, int wr, int wc, int fr, int fq, LAS unsigned char* lds) const {
;     ...
; #pragma unroll
;         for (int bj = 0; bj < 2; ++bj)
; #pragma unroll
;             for (int n = 0; n < 2; ++n) { const int cc = col0 + bj * HALF + n * 16; const f32x4 g4 = *(const f32x4*)(g + cc), b4 = *(const f32x4*)(b + cc);
; #pragma unroll
;                 for (int ai = 0; ai < 2; ++ai)
; #pragma unroll
;                     for (int m = 0; m < 4; ++m) { const int rl = rl0 + ai * HALF + m * 16; const float mean = S2[rl * 2], rstd = S2[rl * 2 + 1];
;                         const f32x4 y = (acc[ai][bj][m][n] - mean) * rstd * g4 + b4; const size_t row = (size_t)(u.pm * BM + rl);
;                         if (of) *(f32x4*)(of + row * DM + cc) = y;
;                         else { u32x2 pk; pk.x = cvt_pk_bf16(y[0], y[1]); pk.y = cvt_pk_bf16(y[2], y[3]); *(u32x2*)(ob + row * LDX + cc) = pk; } }
;                 asm volatile("" ::: "memory"); }
.LBB0_597:
	s_and_b64 vcc, exec, s[0:1]
	s_waitcnt lgkmcnt(0)
	v_sub_f32_e32 v11, v168, v183
	v_sub_f32_e32 v10, v162, v183
	v_sub_f32_e32 v147, v166, v183
	v_sub_f32_e32 v146, v26, v183
	v_pk_mul_f32 v[146:147], v[146:147], v[166:167] op_sel:[0,1]
	v_pk_mul_f32 v[8:9], v[10:11], v[166:167] op_sel:[0,1]
	s_nop 0
	v_pk_fma_f32 v[10:11], v[2:3], v[8:9], v[6:7]
	v_pk_fma_f32 v[8:9], v[0:1], v[146:147], v[4:5]
	v_lshlrev_b64 v[146:147], 13, v[164:165]
	v_lshl_add_u64 v[154:155], s[14:15], 0, v[146:147]
	s_cbranch_vccnz .LBB0_683
	v_lshl_add_u64 v[146:147], v[134:135], 2, v[154:155]
	global_store_dwordx4 v[146:147], v[8:11], off
	v_lshl_add_u64 v[146:147], s[22:23], 0, v[186:187]
	v_lshl_add_u64 v[146:147], v[134:135], 1, v[146:147]
	s_cbranch_execnz .LBB0_600

; __device__ __forceinline__ unsigned cvt_pk_bf16(float lo, float hi) { unsigned r; asm volatile("v_cvt_pk_bf16_f32 %0, %1, %2" : "=v"(r) : "v"(lo), "v"(hi)); return r; }
;     __device__ __forceinline__ void fused(f32x4 (&acc)[2][2][4][2], const Unit& u, int wr, int wc, int fr, int fq, LAS unsigned char* lds) const {
;     ...
; #pragma unroll
;         for (int bj = 0; bj < 2; ++bj)
; #pragma unroll
;             for (int n = 0; n < 2; ++n) { const int cc = col0 + bj * HALF + n * 16; const f32x4 g4 = *(const f32x4*)(g + cc), b4 = *(const f32x4*)(b + cc);
; #pragma unroll
;                 for (int ai = 0; ai < 2; ++ai)
; #pragma unroll
;                     for (int m = 0; m < 4; ++m) { const int rl = rl0 + ai * HALF + m * 16; const float mean = S2[rl * 2], rstd = S2[rl * 2 + 1];
;                         const f32x4 y = (acc[ai][bj][m][n] - mean) * rstd * g4 + b4; const size_t row = (size_t)(u.pm * BM + rl);
;                         if (of) *(f32x4*)(of + row * DM + cc) = y;
;                         else { u32x2 pk; pk.x = cvt_pk_bf16(y[0], y[1]); pk.y = cvt_pk_bf16(y[2], y[3]); *(u32x2*)(ob + row * LDX + cc) = pk; } }
;                 asm volatile("" ::: "memory"); }
.LBB0_600:
	s_and_b64 vcc, exec, s[0:1]
	s_waitcnt lgkmcnt(0)
	v_sub_f32_e32 v151, v180, v64
	v_sub_f32_e32 v150, v170, v64
	v_sub_f32_e32 v11, v182, v64
	v_sub_f32_e32 v10, v172, v64
	v_pk_mul_f32 v[150:151], v[150:151], v[168:169] op_sel:[0,1]
	v_pk_mul_f32 v[8:9], v[10:11], v[168:169] op_sel:[0,1]
	v_pk_fma_f32 v[0:1], v[0:1], v[150:151], v[4:5]
	v_lshlrev_b64 v[4:5], 13, v[174:175]
	v_pk_fma_f32 v[2:3], v[2:3], v[8:9], v[6:7]
	v_lshl_add_u64 v[156:157], s[14:15], 0, v[4:5]
	s_cbranch_vccnz .LBB0_684
	v_lshl_add_u64 v[4:5], v[134:135], 2, v[156:157]
	global_store_dwordx4 v[4:5], v[0:3], off
	v_lshl_add_u64 v[4:5], s[22:23], 0, v[184:185]
	v_lshl_add_u64 v[150:151], v[134:135], 1, v[4:5]
	s_cbranch_execnz .LBB0_603

; __device__ __forceinline__ unsigned cvt_pk_bf16(float lo, float hi) { unsigned r; asm volatile("v_cvt_pk_bf16_f32 %0, %1, %2" : "=v"(r) : "v"(lo), "v"(hi)); return r; }
;     __device__ __forceinline__ void fused(f32x4 (&acc)[2][2][4][2], const Unit& u, int wr, int wc, int fr, int fq, LAS unsigned char* lds) const {
;     ...
; #pragma unroll
;         for (int bj = 0; bj < 2; ++bj)
; #pragma unroll
;             for (int n = 0; n < 2; ++n) { const int cc = col0 + bj * HALF + n * 16; const f32x4 g4 = *(const f32x4*)(g + cc), b4 = *(const f32x4*)(b + cc);
; #pragma unroll
;                 for (int ai = 0; ai < 2; ++ai)
; #pragma unroll
;                     for (int m = 0; m < 4; ++m) { const int rl = rl0 + ai * HALF + m * 16; const float mean = S2[rl * 2], rstd = S2[rl * 2 + 1];
;                         const f32x4 y = (acc[ai][bj][m][n] - mean) * rstd * g4 + b4; const size_t row = (size_t)(u.pm * BM + rl);
;                         if (of) *(f32x4*)(of + row * DM + cc) = y;
;                         else { u32x2 pk; pk.x = cvt_pk_bf16(y[0], y[1]); pk.y = cvt_pk_bf16(y[2], y[3]); *(u32x2*)(ob + row * LDX + cc) = pk; } }
;                 asm volatile("" ::: "memory"); }
.LBB0_603:
	global_load_dwordx4 v[0:3], v[176:177], off offset:64
	global_load_dwordx4 v[4:7], v[178:179], off offset:64
	s_and_b64 vcc, exec, s[0:1]
	s_waitcnt lgkmcnt(0)
	v_sub_f32_e32 v11, v137, v208
	v_sub_f32_e32 v10, v136, v208
	v_sub_f32_e32 v119, v119, v208
	v_sub_f32_e32 v118, v125, v208
	v_pk_mul_f32 v[118:119], v[118:119], v[208:209] op_sel:[0,1]
	v_pk_mul_f32 v[8:9], v[10:11], v[208:209] op_sel:[0,1]
	s_waitcnt vmcnt(0)
	v_pk_fma_f32 v[10:11], v[2:3], v[8:9], v[6:7]
	v_pk_fma_f32 v[8:9], v[0:1], v[118:119], v[4:5]
	s_cbranch_vccnz .LBB0_685
	v_lshl_add_u64 v[118:119], v[134:135], 2, v[138:139]
	global_store_dwordx4 v[118:119], v[8:11], off offset:64
	s_cbranch_execnz .LBB0_606

; __device__ __forceinline__ unsigned cvt_pk_bf16(float lo, float hi) { unsigned r; asm volatile("v_cvt_pk_bf16_f32 %0, %1, %2" : "=v"(r) : "v"(lo), "v"(hi)); return r; }
;     __device__ __forceinline__ void fused(f32x4 (&acc)[2][2][4][2], const Unit& u, int wr, int wc, int fr, int fq, LAS unsigned char* lds) const {
;     ...
; #pragma unroll
;         for (int bj = 0; bj < 2; ++bj)
; #pragma unroll
;             for (int n = 0; n < 2; ++n) { const int cc = col0 + bj * HALF + n * 16; const f32x4 g4 = *(const f32x4*)(g + cc), b4 = *(const f32x4*)(b + cc);
; #pragma unroll
;                 for (int ai = 0; ai < 2; ++ai)
; #pragma unroll
;                     for (int m = 0; m < 4; ++m) { const int rl = rl0 + ai * HALF + m * 16; const float mean = S2[rl * 2], rstd = S2[rl * 2 + 1];
;                         const f32x4 y = (acc[ai][bj][m][n] - mean) * rstd * g4 + b4; const size_t row = (size_t)(u.pm * BM + rl);
;                         if (of) *(f32x4*)(of + row * DM + cc) = y;
;                         else { u32x2 pk; pk.x = cvt_pk_bf16(y[0], y[1]); pk.y = cvt_pk_bf16(y[2], y[3]); *(u32x2*)(ob + row * LDX + cc) = pk; } }
;                 asm volatile("" ::: "memory"); }
.LBB0_606:
	s_and_b64 vcc, exec, s[0:1]
	s_waitcnt lgkmcnt(0)
	v_sub_f32_e32 v11, v115, v210
	v_sub_f32_e32 v10, v114, v210
	v_sub_f32_e32 v103, v103, v210
	v_sub_f32_e32 v102, v109, v210
	v_pk_mul_f32 v[102:103], v[102:103], v[210:211] op_sel:[0,1]
	v_pk_mul_f32 v[8:9], v[10:11], v[210:211] op_sel:[0,1]
	s_nop 0
	v_pk_fma_f32 v[10:11], v[2:3], v[8:9], v[6:7]
	v_pk_fma_f32 v[8:9], v[0:1], v[102:103], v[4:5]
	s_cbranch_vccnz .LBB0_686
	v_lshl_add_u64 v[102:103], v[134:135], 2, v[140:141]
	global_store_dwordx4 v[102:103], v[8:11], off offset:64
	s_cbranch_execnz .LBB0_609

; __device__ __forceinline__ unsigned cvt_pk_bf16(float lo, float hi) { unsigned r; asm volatile("v_cvt_pk_bf16_f32 %0, %1, %2" : "=v"(r) : "v"(lo), "v"(hi)); return r; }
;     __device__ __forceinline__ void fused(f32x4 (&acc)[2][2][4][2], const Unit& u, int wr, int wc, int fr, int fq, LAS unsigned char* lds) const {
;     ...
; #pragma unroll
;         for (int bj = 0; bj < 2; ++bj)
; #pragma unroll
;             for (int n = 0; n < 2; ++n) { const int cc = col0 + bj * HALF + n * 16; const f32x4 g4 = *(const f32x4*)(g + cc), b4 = *(const f32x4*)(b + cc);
; #pragma unroll
;                 for (int ai = 0; ai < 2; ++ai)
; #pragma unroll
;                     for (int m = 0; m < 4; ++m) { const int rl = rl0 + ai * HALF + m * 16; const float mean = S2[rl * 2], rstd = S2[rl * 2 + 1];
;                         const f32x4 y = (acc[ai][bj][m][n] - mean) * rstd * g4 + b4; const size_t row = (size_t)(u.pm * BM + rl);
;                         if (of) *(f32x4*)(of + row * DM + cc) = y;
;                         else { u32x2 pk; pk.x = cvt_pk_bf16(y[0], y[1]); pk.y = cvt_pk_bf16(y[2], y[3]); *(u32x2*)(ob + row * LDX + cc) = pk; } }
;                 asm volatile("" ::: "memory"); }
.LBB0_609:
	s_and_b64 vcc, exec, s[0:1]
	s_waitcnt lgkmcnt(0)
	v_sub_f32_e32 v11, v99, v212
	v_sub_f32_e32 v10, v98, v212
	v_sub_f32_e32 v87, v87, v212
	v_sub_f32_e32 v86, v93, v212
	v_pk_mul_f32 v[86:87], v[86:87], v[212:213] op_sel:[0,1]
	v_pk_mul_f32 v[8:9], v[10:11], v[212:213] op_sel:[0,1]
	s_nop 0
	v_pk_fma_f32 v[10:11], v[2:3], v[8:9], v[6:7]
	v_pk_fma_f32 v[8:9], v[0:1], v[86:87], v[4:5]
	s_cbranch_vccnz .LBB0_687
	v_lshl_add_u64 v[86:87], v[134:135], 2, v[142:143]
	global_store_dwordx4 v[86:87], v[8:11], off offset:64
	s_cbranch_execnz .LBB0_612

; __device__ __forceinline__ unsigned cvt_pk_bf16(float lo, float hi) { unsigned r; asm volatile("v_cvt_pk_bf16_f32 %0, %1, %2" : "=v"(r) : "v"(lo), "v"(hi)); return r; }
;     __device__ __forceinline__ void fused(f32x4 (&acc)[2][2][4][2], const Unit& u, int wr, int wc, int fr, int fq, LAS unsigned char* lds) const {
;     ...
; #pragma unroll
;         for (int bj = 0; bj < 2; ++bj)
; #pragma unroll
;             for (int n = 0; n < 2; ++n) { const int cc = col0 + bj * HALF + n * 16; const f32x4 g4 = *(const f32x4*)(g + cc), b4 = *(const f32x4*)(b + cc);
; #pragma unroll
;                 for (int ai = 0; ai < 2; ++ai)
; #pragma unroll
;                     for (int m = 0; m < 4; ++m) { const int rl = rl0 + ai * HALF + m * 16; const float mean = S2[rl * 2], rstd = S2[rl * 2 + 1];
;                         const f32x4 y = (acc[ai][bj][m][n] - mean) * rstd * g4 + b4; const size_t row = (size_t)(u.pm * BM + rl);
;                         if (of) *(f32x4*)(of + row * DM + cc) = y;
;                         else { u32x2 pk; pk.x = cvt_pk_bf16(y[0], y[1]); pk.y = cvt_pk_bf16(y[2], y[3]); *(u32x2*)(ob + row * LDX + cc) = pk; } }
;                 asm volatile("" ::: "memory"); }
.LBB0_612:
	s_and_b64 vcc, exec, s[0:1]
	s_waitcnt lgkmcnt(0)
	v_sub_f32_e32 v11, v83, v214
	v_sub_f32_e32 v10, v82, v214
	v_sub_f32_e32 v71, v71, v214
	v_sub_f32_e32 v70, v77, v214
	v_pk_mul_f32 v[70:71], v[70:71], v[214:215] op_sel:[0,1]
	v_pk_mul_f32 v[8:9], v[10:11], v[214:215] op_sel:[0,1]
	s_nop 0
	v_pk_fma_f32 v[10:11], v[2:3], v[8:9], v[6:7]
	v_pk_fma_f32 v[8:9], v[0:1], v[70:71], v[4:5]
	s_cbranch_vccnz .LBB0_688
	v_lshl_add_u64 v[70:71], v[134:135], 2, v[144:145]
	global_store_dwordx4 v[70:71], v[8:11], off offset:64
	s_cbranch_execnz .LBB0_615

; __device__ __forceinline__ unsigned cvt_pk_bf16(float lo, float hi) { unsigned r; asm volatile("v_cvt_pk_bf16_f32 %0, %1, %2" : "=v"(r) : "v"(lo), "v"(hi)); return r; }
;     __device__ __forceinline__ void fused(f32x4 (&acc)[2][2][4][2], const Unit& u, int wr, int wc, int fr, int fq, LAS unsigned char* lds) const {
;     ...
; #pragma unroll
;         for (int bj = 0; bj < 2; ++bj)
; #pragma unroll
;             for (int n = 0; n < 2; ++n) { const int cc = col0 + bj * HALF + n * 16; const f32x4 g4 = *(const f32x4*)(g + cc), b4 = *(const f32x4*)(b + cc);
; #pragma unroll
;                 for (int ai = 0; ai < 2; ++ai)
; #pragma unroll
;                     for (int m = 0; m < 4; ++m) { const int rl = rl0 + ai * HALF + m * 16; const float mean = S2[rl * 2], rstd = S2[rl * 2 + 1];
;                         const f32x4 y = (acc[ai][bj][m][n] - mean) * rstd * g4 + b4; const size_t row = (size_t)(u.pm * BM + rl);
;                         if (of) *(f32x4*)(of + row * DM + cc) = y;
;                         else { u32x2 pk; pk.x = cvt_pk_bf16(y[0], y[1]); pk.y = cvt_pk_bf16(y[2], y[3]); *(u32x2*)(ob + row * LDX + cc) = pk; } }
;                 asm volatile("" ::: "memory"); }
.LBB0_615:
	s_and_b64 vcc, exec, s[0:1]
	s_waitcnt lgkmcnt(0)
	v_sub_f32_e32 v11, v67, v246
	v_sub_f32_e32 v10, v66, v246
	v_sub_f32_e32 v53, v53, v246
	v_sub_f32_e32 v52, v59, v246
	v_pk_mul_f32 v[52:53], v[52:53], v[246:247] op_sel:[0,1]
	v_pk_mul_f32 v[8:9], v[10:11], v[246:247] op_sel:[0,1]
	s_nop 0
	v_pk_fma_f32 v[10:11], v[2:3], v[8:9], v[6:7]
	v_pk_fma_f32 v[8:9], v[0:1], v[52:53], v[4:5]
	s_cbranch_vccnz .LBB0_689
	v_lshl_add_u64 v[52:53], v[134:135], 2, v[148:149]
	global_store_dwordx4 v[52:53], v[8:11], off offset:64
	s_cbranch_execnz .LBB0_618

; __device__ __forceinline__ unsigned cvt_pk_bf16(float lo, float hi) { unsigned r; asm volatile("v_cvt_pk_bf16_f32 %0, %1, %2" : "=v"(r) : "v"(lo), "v"(hi)); return r; }
;     __device__ __forceinline__ void fused(f32x4 (&acc)[2][2][4][2], const Unit& u, int wr, int wc, int fr, int fq, LAS unsigned char* lds) const {
;     ...
; #pragma unroll
;         for (int bj = 0; bj < 2; ++bj)
; #pragma unroll
;             for (int n = 0; n < 2; ++n) { const int cc = col0 + bj * HALF + n * 16; const f32x4 g4 = *(const f32x4*)(g + cc), b4 = *(const f32x4*)(b + cc);
; #pragma unroll
;                 for (int ai = 0; ai < 2; ++ai)
; #pragma unroll
;                     for (int m = 0; m < 4; ++m) { const int rl = rl0 + ai * HALF + m * 16; const float mean = S2[rl * 2], rstd = S2[rl * 2 + 1];
;                         const f32x4 y = (acc[ai][bj][m][n] - mean) * rstd * g4 + b4; const size_t row = (size_t)(u.pm * BM + rl);
;                         if (of) *(f32x4*)(of + row * DM + cc) = y;
;                         else { u32x2 pk; pk.x = cvt_pk_bf16(y[0], y[1]); pk.y = cvt_pk_bf16(y[2], y[3]); *(u32x2*)(ob + row * LDX + cc) = pk; } }
;                 asm volatile("" ::: "memory"); }
.LBB0_618:
	s_and_b64 vcc, exec, s[0:1]
	s_waitcnt lgkmcnt(0)
	v_sub_f32_e32 v11, v49, v181
	v_sub_f32_e32 v10, v48, v181
	v_sub_f32_e32 v37, v37, v181
	v_sub_f32_e32 v36, v43, v181
	v_pk_mul_f32 v[36:37], v[36:37], v[160:161] op_sel:[0,1]
	v_pk_mul_f32 v[8:9], v[10:11], v[160:161] op_sel:[0,1]
	s_nop 0
	v_pk_fma_f32 v[10:11], v[2:3], v[8:9], v[6:7]
	v_pk_fma_f32 v[8:9], v[0:1], v[36:37], v[4:5]
	s_cbranch_vccnz .LBB0_690
	v_lshl_add_u64 v[36:37], v[134:135], 2, v[152:153]
	global_store_dwordx4 v[36:37], v[8:11], off offset:64
	s_cbranch_execnz .LBB0_621

; __device__ __forceinline__ unsigned cvt_pk_bf16(float lo, float hi) { unsigned r; asm volatile("v_cvt_pk_bf16_f32 %0, %1, %2" : "=v"(r) : "v"(lo), "v"(hi)); return r; }
;     __device__ __forceinline__ void fused(f32x4 (&acc)[2][2][4][2], const Unit& u, int wr, int wc, int fr, int fq, LAS unsigned char* lds) const {
;     ...
; #pragma unroll
;         for (int bj = 0; bj < 2; ++bj)
; #pragma unroll
;             for (int n = 0; n < 2; ++n) { const int cc = col0 + bj * HALF + n * 16; const f32x4 g4 = *(const f32x4*)(g + cc), b4 = *(const f32x4*)(b + cc);
; #pragma unroll
;                 for (int ai = 0; ai < 2; ++ai)
; #pragma unroll
;                     for (int m = 0; m < 4; ++m) { const int rl = rl0 + ai * HALF + m * 16; const float mean = S2[rl * 2], rstd = S2[rl * 2 + 1];
;                         const f32x4 y = (acc[ai][bj][m][n] - mean) * rstd * g4 + b4; const size_t row = (size_t)(u.pm * BM + rl);
;                         if (of) *(f32x4*)(of + row * DM + cc) = y;
;                         else { u32x2 pk; pk.x = cvt_pk_bf16(y[0], y[1]); pk.y = cvt_pk_bf16(y[2], y[3]); *(u32x2*)(ob + row * LDX + cc) = pk; } }
;                 asm volatile("" ::: "memory"); }
.LBB0_621:
	s_and_b64 vcc, exec, s[0:1]
	s_waitcnt lgkmcnt(0)
	v_sub_f32_e32 v11, v33, v183
	v_sub_f32_e32 v10, v32, v183
	v_sub_f32_e32 v33, v163, v183
	v_sub_f32_e32 v32, v27, v183
	v_pk_mul_f32 v[26:27], v[32:33], v[166:167] op_sel:[0,1]
	v_pk_mul_f32 v[8:9], v[10:11], v[166:167] op_sel:[0,1]
	s_nop 0
	v_pk_fma_f32 v[10:11], v[2:3], v[8:9], v[6:7]
	v_pk_fma_f32 v[8:9], v[0:1], v[26:27], v[4:5]
	s_cbranch_vccnz .LBB0_691
	v_lshl_add_u64 v[26:27], v[134:135], 2, v[154:155]
	global_store_dwordx4 v[26:27], v[8:11], off offset:64
	s_cbranch_execnz .LBB0_624

; __device__ __forceinline__ unsigned cvt_pk_bf16(float lo, float hi) { unsigned r; asm volatile("v_cvt_pk_bf16_f32 %0, %1, %2" : "=v"(r) : "v"(lo), "v"(hi)); return r; }
;     __device__ __forceinline__ void fused(f32x4 (&acc)[2][2][4][2], const Unit& u, int wr, int wc, int fr, int fq, LAS unsigned char* lds) const {
;     ...
; #pragma unroll
;         for (int bj = 0; bj < 2; ++bj)
; #pragma unroll
;             for (int n = 0; n < 2; ++n) { const int cc = col0 + bj * HALF + n * 16; const f32x4 g4 = *(const f32x4*)(g + cc), b4 = *(const f32x4*)(b + cc);
; #pragma unroll
;                 for (int ai = 0; ai < 2; ++ai)
; #pragma unroll
;                     for (int m = 0; m < 4; ++m) { const int rl = rl0 + ai * HALF + m * 16; const float mean = S2[rl * 2], rstd = S2[rl * 2 + 1];
;                         const f32x4 y = (acc[ai][bj][m][n] - mean) * rstd * g4 + b4; const size_t row = (size_t)(u.pm * BM + rl);
;                         if (of) *(f32x4*)(of + row * DM + cc) = y;
;                         else { u32x2 pk; pk.x = cvt_pk_bf16(y[0], y[1]); pk.y = cvt_pk_bf16(y[2], y[3]); *(u32x2*)(ob + row * LDX + cc) = pk; } }
;                 asm volatile("" ::: "memory"); }
.LBB0_624:
	s_and_b64 vcc, exec, s[0:1]
	s_waitcnt lgkmcnt(0)
	v_sub_f32_e32 v11, v23, v64
	v_sub_f32_e32 v10, v22, v64
	v_sub_f32_e32 v23, v173, v64
	v_sub_f32_e32 v22, v171, v64
	v_pk_mul_f32 v[22:23], v[22:23], v[168:169] op_sel:[0,1]
	v_pk_mul_f32 v[8:9], v[10:11], v[168:169] op_sel:[0,1]
	v_pk_fma_f32 v[0:1], v[0:1], v[22:23], v[4:5]
	v_pk_fma_f32 v[2:3], v[2:3], v[8:9], v[6:7]
	s_cbranch_vccnz .LBB0_692
	v_lshl_add_u64 v[4:5], v[134:135], 2, v[156:157]
	global_store_dwordx4 v[4:5], v[0:3], off offset:64
	s_cbranch_execnz .LBB0_627

; __device__ __forceinline__ unsigned cvt_pk_bf16(float lo, float hi) { unsigned r; asm volatile("v_cvt_pk_bf16_f32 %0, %1, %2" : "=v"(r) : "v"(lo), "v"(hi)); return r; }
;     __device__ __forceinline__ void fused(f32x4 (&acc)[2][2][4][2], const Unit& u, int wr, int wc, int fr, int fq, LAS unsigned char* lds) const {
;     ...
; #pragma unroll
;         for (int bj = 0; bj < 2; ++bj)
; #pragma unroll
;             for (int n = 0; n < 2; ++n) { const int cc = col0 + bj * HALF + n * 16; const f32x4 g4 = *(const f32x4*)(g + cc), b4 = *(const f32x4*)(b + cc);
; #pragma unroll
;                 for (int ai = 0; ai < 2; ++ai)
; #pragma unroll
;                     for (int m = 0; m < 4; ++m) { const int rl = rl0 + ai * HALF + m * 16; const float mean = S2[rl * 2], rstd = S2[rl * 2 + 1];
;                         const f32x4 y = (acc[ai][bj][m][n] - mean) * rstd * g4 + b4; const size_t row = (size_t)(u.pm * BM + rl);
;                         if (of) *(f32x4*)(of + row * DM + cc) = y;
;                         else { u32x2 pk; pk.x = cvt_pk_bf16(y[0], y[1]); pk.y = cvt_pk_bf16(y[2], y[3]); *(u32x2*)(ob + row * LDX + cc) = pk; } }
;                 asm volatile("" ::: "memory"); }
.LBB0_627:
	global_load_dwordx4 v[0:3], v[176:177], off offset:512
	global_load_dwordx4 v[4:7], v[178:179], off offset:512
	s_and_b64 vcc, exec, s[0:1]
	s_waitcnt lgkmcnt(0)
	v_sub_f32_e32 v11, v129, v208
	v_sub_f32_e32 v10, v128, v208
	v_sub_f32_e32 v23, v127, v208
	v_sub_f32_e32 v22, v126, v208
	v_pk_mul_f32 v[22:23], v[22:23], v[208:209] op_sel:[0,1]
	v_pk_mul_f32 v[8:9], v[10:11], v[208:209] op_sel:[0,1]
	s_waitcnt vmcnt(0)
	v_pk_fma_f32 v[10:11], v[2:3], v[8:9], v[6:7]
	v_pk_fma_f32 v[8:9], v[0:1], v[22:23], v[4:5]
	s_cbranch_vccnz .LBB0_693
	v_lshl_add_u64 v[22:23], v[134:135], 2, v[138:139]
	global_store_dwordx4 v[22:23], v[8:11], off offset:512
	s_cbranch_execnz .LBB0_630

; __device__ __forceinline__ unsigned cvt_pk_bf16(float lo, float hi) { unsigned r; asm volatile("v_cvt_pk_bf16_f32 %0, %1, %2" : "=v"(r) : "v"(lo), "v"(hi)); return r; }
;     __device__ __forceinline__ void fused(f32x4 (&acc)[2][2][4][2], const Unit& u, int wr, int wc, int fr, int fq, LAS unsigned char* lds) const {
;     ...
; #pragma unroll
;         for (int bj = 0; bj < 2; ++bj)
; #pragma unroll
;             for (int n = 0; n < 2; ++n) { const int cc = col0 + bj * HALF + n * 16; const f32x4 g4 = *(const f32x4*)(g + cc), b4 = *(const f32x4*)(b + cc);
; #pragma unroll
;                 for (int ai = 0; ai < 2; ++ai)
; #pragma unroll
;                     for (int m = 0; m < 4; ++m) { const int rl = rl0 + ai * HALF + m * 16; const float mean = S2[rl * 2], rstd = S2[rl * 2 + 1];
;                         const f32x4 y = (acc[ai][bj][m][n] - mean) * rstd * g4 + b4; const size_t row = (size_t)(u.pm * BM + rl);
;                         if (of) *(f32x4*)(of + row * DM + cc) = y;
;                         else { u32x2 pk; pk.x = cvt_pk_bf16(y[0], y[1]); pk.y = cvt_pk_bf16(y[2], y[3]); *(u32x2*)(ob + row * LDX + cc) = pk; } }
;                 asm volatile("" ::: "memory"); }
.LBB0_630:
	s_and_b64 vcc, exec, s[0:1]
	s_waitcnt lgkmcnt(0)
	v_sub_f32_e32 v11, v113, v210
	v_sub_f32_e32 v10, v112, v210
	v_sub_f32_e32 v23, v111, v210
	v_sub_f32_e32 v22, v110, v210
	v_pk_mul_f32 v[22:23], v[22:23], v[210:211] op_sel:[0,1]
	v_pk_mul_f32 v[8:9], v[10:11], v[210:211] op_sel:[0,1]
	s_nop 0
	v_pk_fma_f32 v[10:11], v[2:3], v[8:9], v[6:7]
	v_pk_fma_f32 v[8:9], v[0:1], v[22:23], v[4:5]
	s_cbranch_vccnz .LBB0_694
	v_lshl_add_u64 v[22:23], v[134:135], 2, v[140:141]
	global_store_dwordx4 v[22:23], v[8:11], off offset:512
	s_cbranch_execnz .LBB0_633

; __device__ __forceinline__ unsigned cvt_pk_bf16(float lo, float hi) { unsigned r; asm volatile("v_cvt_pk_bf16_f32 %0, %1, %2" : "=v"(r) : "v"(lo), "v"(hi)); return r; }
;     __device__ __forceinline__ void fused(f32x4 (&acc)[2][2][4][2], const Unit& u, int wr, int wc, int fr, int fq, LAS unsigned char* lds) const {
;     ...
; #pragma unroll
;         for (int bj = 0; bj < 2; ++bj)
; #pragma unroll
;             for (int n = 0; n < 2; ++n) { const int cc = col0 + bj * HALF + n * 16; const f32x4 g4 = *(const f32x4*)(g + cc), b4 = *(const f32x4*)(b + cc);
; #pragma unroll
;                 for (int ai = 0; ai < 2; ++ai)
; #pragma unroll
;                     for (int m = 0; m < 4; ++m) { const int rl = rl0 + ai * HALF + m * 16; const float mean = S2[rl * 2], rstd = S2[rl * 2 + 1];
;                         const f32x4 y = (acc[ai][bj][m][n] - mean) * rstd * g4 + b4; const size_t row = (size_t)(u.pm * BM + rl);
;                         if (of) *(f32x4*)(of + row * DM + cc) = y;
;                         else { u32x2 pk; pk.x = cvt_pk_bf16(y[0], y[1]); pk.y = cvt_pk_bf16(y[2], y[3]); *(u32x2*)(ob + row * LDX + cc) = pk; } }
;                 asm volatile("" ::: "memory"); }
.LBB0_633:
	s_and_b64 vcc, exec, s[0:1]
	s_waitcnt lgkmcnt(0)
	v_sub_f32_e32 v11, v97, v212
	v_sub_f32_e32 v10, v96, v212
	v_sub_f32_e32 v23, v95, v212
	v_sub_f32_e32 v22, v94, v212
	v_pk_mul_f32 v[22:23], v[22:23], v[212:213] op_sel:[0,1]
	v_pk_mul_f32 v[8:9], v[10:11], v[212:213] op_sel:[0,1]
	s_nop 0
	v_pk_fma_f32 v[10:11], v[2:3], v[8:9], v[6:7]
	v_pk_fma_f32 v[8:9], v[0:1], v[22:23], v[4:5]
	s_cbranch_vccnz .LBB0_695
	v_lshl_add_u64 v[22:23], v[134:135], 2, v[142:143]
	global_store_dwordx4 v[22:23], v[8:11], off offset:512
	s_cbranch_execnz .LBB0_636

; __device__ __forceinline__ unsigned cvt_pk_bf16(float lo, float hi) { unsigned r; asm volatile("v_cvt_pk_bf16_f32 %0, %1, %2" : "=v"(r) : "v"(lo), "v"(hi)); return r; }
;     __device__ __forceinline__ void fused(f32x4 (&acc)[2][2][4][2], const Unit& u, int wr, int wc, int fr, int fq, LAS unsigned char* lds) const {
;     ...
; #pragma unroll
;         for (int bj = 0; bj < 2; ++bj)
; #pragma unroll
;             for (int n = 0; n < 2; ++n) { const int cc = col0 + bj * HALF + n * 16; const f32x4 g4 = *(const f32x4*)(g + cc), b4 = *(const f32x4*)(b + cc);
; #pragma unroll
;                 for (int ai = 0; ai < 2; ++ai)
; #pragma unroll
;                     for (int m = 0; m < 4; ++m) { const int rl = rl0 + ai * HALF + m * 16; const float mean = S2[rl * 2], rstd = S2[rl * 2 + 1];
;                         const f32x4 y = (acc[ai][bj][m][n] - mean) * rstd * g4 + b4; const size_t row = (size_t)(u.pm * BM + rl);
;                         if (of) *(f32x4*)(of + row * DM + cc) = y;
;                         else { u32x2 pk; pk.x = cvt_pk_bf16(y[0], y[1]); pk.y = cvt_pk_bf16(y[2], y[3]); *(u32x2*)(ob + row * LDX + cc) = pk; } }
;                 asm volatile("" ::: "memory"); }
.LBB0_636:
	s_and_b64 vcc, exec, s[0:1]
	s_waitcnt lgkmcnt(0)
	v_sub_f32_e32 v11, v81, v214
	v_sub_f32_e32 v10, v80, v214
	v_sub_f32_e32 v23, v79, v214
	v_sub_f32_e32 v22, v78, v214
	v_pk_mul_f32 v[22:23], v[22:23], v[214:215] op_sel:[0,1]
	v_pk_mul_f32 v[8:9], v[10:11], v[214:215] op_sel:[0,1]
	s_nop 0
	v_pk_fma_f32 v[10:11], v[2:3], v[8:9], v[6:7]
	v_pk_fma_f32 v[8:9], v[0:1], v[22:23], v[4:5]
	s_cbranch_vccnz .LBB0_696
	v_lshl_add_u64 v[22:23], v[134:135], 2, v[144:145]
	global_store_dwordx4 v[22:23], v[8:11], off offset:512
	s_cbranch_execnz .LBB0_639

; __device__ __forceinline__ unsigned cvt_pk_bf16(float lo, float hi) { unsigned r; asm volatile("v_cvt_pk_bf16_f32 %0, %1, %2" : "=v"(r) : "v"(lo), "v"(hi)); return r; }
;     __device__ __forceinline__ void fused(f32x4 (&acc)[2][2][4][2], const Unit& u, int wr, int wc, int fr, int fq, LAS unsigned char* lds) const {
;     ...
; #pragma unroll
;         for (int bj = 0; bj < 2; ++bj)
; #pragma unroll
;             for (int n = 0; n < 2; ++n) { const int cc = col0 + bj * HALF + n * 16; const f32x4 g4 = *(const f32x4*)(g + cc), b4 = *(const f32x4*)(b + cc);
; #pragma unroll
;                 for (int ai = 0; ai < 2; ++ai)
; #pragma unroll
;                     for (int m = 0; m < 4; ++m) { const int rl = rl0 + ai * HALF + m * 16; const float mean = S2[rl * 2], rstd = S2[rl * 2 + 1];
;                         const f32x4 y = (acc[ai][bj][m][n] - mean) * rstd * g4 + b4; const size_t row = (size_t)(u.pm * BM + rl);
;                         if (of) *(f32x4*)(of + row * DM + cc) = y;
;                         else { u32x2 pk; pk.x = cvt_pk_bf16(y[0], y[1]); pk.y = cvt_pk_bf16(y[2], y[3]); *(u32x2*)(ob + row * LDX + cc) = pk; } }
;                 asm volatile("" ::: "memory"); }
.LBB0_639:
	s_and_b64 vcc, exec, s[0:1]
	s_waitcnt lgkmcnt(0)
	v_sub_f32_e32 v11, v63, v246
	v_sub_f32_e32 v10, v62, v246
	v_sub_f32_e32 v23, v61, v246
	v_sub_f32_e32 v22, v60, v246
	v_pk_mul_f32 v[22:23], v[22:23], v[246:247] op_sel:[0,1]
	v_pk_mul_f32 v[8:9], v[10:11], v[246:247] op_sel:[0,1]
	s_nop 0
	v_pk_fma_f32 v[10:11], v[2:3], v[8:9], v[6:7]
	v_pk_fma_f32 v[8:9], v[0:1], v[22:23], v[4:5]
	s_cbranch_vccnz .LBB0_697
	v_lshl_add_u64 v[22:23], v[134:135], 2, v[148:149]
	global_store_dwordx4 v[22:23], v[8:11], off offset:512
	s_cbranch_execnz .LBB0_642

; __device__ __forceinline__ unsigned cvt_pk_bf16(float lo, float hi) { unsigned r; asm volatile("v_cvt_pk_bf16_f32 %0, %1, %2" : "=v"(r) : "v"(lo), "v"(hi)); return r; }
;     __device__ __forceinline__ void fused(f32x4 (&acc)[2][2][4][2], const Unit& u, int wr, int wc, int fr, int fq, LAS unsigned char* lds) const {
;     ...
; #pragma unroll
;         for (int bj = 0; bj < 2; ++bj)
; #pragma unroll
;             for (int n = 0; n < 2; ++n) { const int cc = col0 + bj * HALF + n * 16; const f32x4 g4 = *(const f32x4*)(g + cc), b4 = *(const f32x4*)(b + cc);
; #pragma unroll
;                 for (int ai = 0; ai < 2; ++ai)
; #pragma unroll
;                     for (int m = 0; m < 4; ++m) { const int rl = rl0 + ai * HALF + m * 16; const float mean = S2[rl * 2], rstd = S2[rl * 2 + 1];
;                         const f32x4 y = (acc[ai][bj][m][n] - mean) * rstd * g4 + b4; const size_t row = (size_t)(u.pm * BM + rl);
;                         if (of) *(f32x4*)(of + row * DM + cc) = y;
;                         else { u32x2 pk; pk.x = cvt_pk_bf16(y[0], y[1]); pk.y = cvt_pk_bf16(y[2], y[3]); *(u32x2*)(ob + row * LDX + cc) = pk; } }
;                 asm volatile("" ::: "memory"); }
.LBB0_642:
	s_and_b64 vcc, exec, s[0:1]
	s_waitcnt lgkmcnt(0)
	v_sub_f32_e32 v11, v47, v181
	v_sub_f32_e32 v10, v46, v181
	v_sub_f32_e32 v23, v45, v181
	v_sub_f32_e32 v22, v44, v181
	v_pk_mul_f32 v[22:23], v[22:23], v[160:161] op_sel:[0,1]
	v_pk_mul_f32 v[8:9], v[10:11], v[160:161] op_sel:[0,1]
	s_nop 0
	v_pk_fma_f32 v[10:11], v[2:3], v[8:9], v[6:7]
	v_pk_fma_f32 v[8:9], v[0:1], v[22:23], v[4:5]
	s_cbranch_vccnz .LBB0_698
	v_lshl_add_u64 v[22:23], v[134:135], 2, v[152:153]
	global_store_dwordx4 v[22:23], v[8:11], off offset:512
	s_cbranch_execnz .LBB0_645

; __device__ __forceinline__ unsigned cvt_pk_bf16(float lo, float hi) { unsigned r; asm volatile("v_cvt_pk_bf16_f32 %0, %1, %2" : "=v"(r) : "v"(lo), "v"(hi)); return r; }
;     __device__ __forceinline__ void fused(f32x4 (&acc)[2][2][4][2], const Unit& u, int wr, int wc, int fr, int fq, LAS unsigned char* lds) const {
;     ...
; #pragma unroll
;         for (int bj = 0; bj < 2; ++bj)
; #pragma unroll
;             for (int n = 0; n < 2; ++n) { const int cc = col0 + bj * HALF + n * 16; const f32x4 g4 = *(const f32x4*)(g + cc), b4 = *(const f32x4*)(b + cc);
; #pragma unroll
;                 for (int ai = 0; ai < 2; ++ai)
; #pragma unroll
;                     for (int m = 0; m < 4; ++m) { const int rl = rl0 + ai * HALF + m * 16; const float mean = S2[rl * 2], rstd = S2[rl * 2 + 1];
;                         const f32x4 y = (acc[ai][bj][m][n] - mean) * rstd * g4 + b4; const size_t row = (size_t)(u.pm * BM + rl);
;                         if (of) *(f32x4*)(of + row * DM + cc) = y;
;                         else { u32x2 pk; pk.x = cvt_pk_bf16(y[0], y[1]); pk.y = cvt_pk_bf16(y[2], y[3]); *(u32x2*)(ob + row * LDX + cc) = pk; } }
;                 asm volatile("" ::: "memory"); }
.LBB0_645:
	s_and_b64 vcc, exec, s[0:1]
	s_waitcnt lgkmcnt(0)
	v_sub_f32_e32 v11, v31, v183
	v_sub_f32_e32 v10, v30, v183
	v_sub_f32_e32 v23, v29, v183
	v_sub_f32_e32 v22, v28, v183
	v_pk_mul_f32 v[22:23], v[22:23], v[166:167] op_sel:[0,1]
	v_pk_mul_f32 v[8:9], v[10:11], v[166:167] op_sel:[0,1]
	s_nop 0
	v_pk_fma_f32 v[10:11], v[2:3], v[8:9], v[6:7]
	v_pk_fma_f32 v[8:9], v[0:1], v[22:23], v[4:5]
	s_cbranch_vccnz .LBB0_699
	v_lshl_add_u64 v[22:23], v[134:135], 2, v[154:155]
	global_store_dwordx4 v[22:23], v[8:11], off offset:512
	s_cbranch_execnz .LBB0_648

; __device__ __forceinline__ unsigned cvt_pk_bf16(float lo, float hi) { unsigned r; asm volatile("v_cvt_pk_bf16_f32 %0, %1, %2" : "=v"(r) : "v"(lo), "v"(hi)); return r; }
;     __device__ __forceinline__ void fused(f32x4 (&acc)[2][2][4][2], const Unit& u, int wr, int wc, int fr, int fq, LAS unsigned char* lds) const {
;     ...
; #pragma unroll
;         for (int bj = 0; bj < 2; ++bj)
; #pragma unroll
;             for (int n = 0; n < 2; ++n) { const int cc = col0 + bj * HALF + n * 16; const f32x4 g4 = *(const f32x4*)(g + cc), b4 = *(const f32x4*)(b + cc);
; #pragma unroll
;                 for (int ai = 0; ai < 2; ++ai)
; #pragma unroll
;                     for (int m = 0; m < 4; ++m) { const int rl = rl0 + ai * HALF + m * 16; const float mean = S2[rl * 2], rstd = S2[rl * 2 + 1];
;                         const f32x4 y = (acc[ai][bj][m][n] - mean) * rstd * g4 + b4; const size_t row = (size_t)(u.pm * BM + rl);
;                         if (of) *(f32x4*)(of + row * DM + cc) = y;
;                         else { u32x2 pk; pk.x = cvt_pk_bf16(y[0], y[1]); pk.y = cvt_pk_bf16(y[2], y[3]); *(u32x2*)(ob + row * LDX + cc) = pk; } }
;                 asm volatile("" ::: "memory"); }
.LBB0_648:
	s_and_b64 vcc, exec, s[0:1]
	s_waitcnt lgkmcnt(0)
	v_sub_f32_e32 v11, v21, v64
	v_sub_f32_e32 v10, v20, v64
	v_sub_f32_e32 v17, v17, v64
	v_sub_f32_e32 v16, v16, v64
	v_pk_mul_f32 v[16:17], v[16:17], v[168:169] op_sel:[0,1]
	v_pk_mul_f32 v[8:9], v[10:11], v[168:169] op_sel:[0,1]
	v_pk_fma_f32 v[0:1], v[0:1], v[16:17], v[4:5]
	v_pk_fma_f32 v[2:3], v[2:3], v[8:9], v[6:7]
	s_cbranch_vccnz .LBB0_700
	v_lshl_add_u64 v[4:5], v[134:135], 2, v[156:157]
	global_store_dwordx4 v[4:5], v[0:3], off offset:512
	s_cbranch_execnz .LBB0_651

; __device__ __forceinline__ unsigned cvt_pk_bf16(float lo, float hi) { unsigned r; asm volatile("v_cvt_pk_bf16_f32 %0, %1, %2" : "=v"(r) : "v"(lo), "v"(hi)); return r; }
;     __device__ __forceinline__ void fused(f32x4 (&acc)[2][2][4][2], const Unit& u, int wr, int wc, int fr, int fq, LAS unsigned char* lds) const {
;     ...
; #pragma unroll
;         for (int bj = 0; bj < 2; ++bj)
; #pragma unroll
;             for (int n = 0; n < 2; ++n) { const int cc = col0 + bj * HALF + n * 16; const f32x4 g4 = *(const f32x4*)(g + cc), b4 = *(const f32x4*)(b + cc);
; #pragma unroll
;                 for (int ai = 0; ai < 2; ++ai)
; #pragma unroll
;                     for (int m = 0; m < 4; ++m) { const int rl = rl0 + ai * HALF + m * 16; const float mean = S2[rl * 2], rstd = S2[rl * 2 + 1];
;                         const f32x4 y = (acc[ai][bj][m][n] - mean) * rstd * g4 + b4; const size_t row = (size_t)(u.pm * BM + rl);
;                         if (of) *(f32x4*)(of + row * DM + cc) = y;
;                         else { u32x2 pk; pk.x = cvt_pk_bf16(y[0], y[1]); pk.y = cvt_pk_bf16(y[2], y[3]); *(u32x2*)(ob + row * LDX + cc) = pk; } }
;                 asm volatile("" ::: "memory"); }
.LBB0_651:
	global_load_dwordx4 v[0:3], v[176:177], off offset:576
	global_load_dwordx4 v[4:7], v[178:179], off offset:576
	s_and_b64 vcc, exec, s[0:1]
	s_waitcnt lgkmcnt(0)
	v_sub_f32_e32 v11, v123, v208
	v_sub_f32_e32 v10, v122, v208
	v_sub_f32_e32 v17, v117, v208
	v_sub_f32_e32 v16, v116, v208
	v_pk_mul_f32 v[16:17], v[16:17], v[208:209] op_sel:[0,1]
	v_pk_mul_f32 v[8:9], v[10:11], v[208:209] op_sel:[0,1]
	s_waitcnt vmcnt(0)
	v_pk_fma_f32 v[10:11], v[2:3], v[8:9], v[6:7]
	v_pk_fma_f32 v[8:9], v[0:1], v[16:17], v[4:5]
	s_cbranch_vccnz .LBB0_701
	v_lshl_add_u64 v[16:17], v[134:135], 2, v[138:139]
	global_store_dwordx4 v[16:17], v[8:11], off offset:576
	s_cbranch_execnz .LBB0_654

; __device__ __forceinline__ unsigned cvt_pk_bf16(float lo, float hi) { unsigned r; asm volatile("v_cvt_pk_bf16_f32 %0, %1, %2" : "=v"(r) : "v"(lo), "v"(hi)); return r; }
;     __device__ __forceinline__ void fused(f32x4 (&acc)[2][2][4][2], const Unit& u, int wr, int wc, int fr, int fq, LAS unsigned char* lds) const {
;     ...
; #pragma unroll
;         for (int bj = 0; bj < 2; ++bj)
; #pragma unroll
;             for (int n = 0; n < 2; ++n) { const int cc = col0 + bj * HALF + n * 16; const f32x4 g4 = *(const f32x4*)(g + cc), b4 = *(const f32x4*)(b + cc);
; #pragma unroll
;                 for (int ai = 0; ai < 2; ++ai)
; #pragma unroll
;                     for (int m = 0; m < 4; ++m) { const int rl = rl0 + ai * HALF + m * 16; const float mean = S2[rl * 2], rstd = S2[rl * 2 + 1];
;                         const f32x4 y = (acc[ai][bj][m][n] - mean) * rstd * g4 + b4; const size_t row = (size_t)(u.pm * BM + rl);
;                         if (of) *(f32x4*)(of + row * DM + cc) = y;
;                         else { u32x2 pk; pk.x = cvt_pk_bf16(y[0], y[1]); pk.y = cvt_pk_bf16(y[2], y[3]); *(u32x2*)(ob + row * LDX + cc) = pk; } }
;                 asm volatile("" ::: "memory"); }
.LBB0_654:
	s_and_b64 vcc, exec, s[0:1]
	s_waitcnt lgkmcnt(0)
	v_sub_f32_e32 v11, v107, v210
	v_sub_f32_e32 v10, v106, v210
	v_sub_f32_e32 v17, v101, v210
	v_sub_f32_e32 v16, v100, v210
	v_pk_mul_f32 v[16:17], v[16:17], v[210:211] op_sel:[0,1]
	v_pk_mul_f32 v[8:9], v[10:11], v[210:211] op_sel:[0,1]
	s_nop 0
	v_pk_fma_f32 v[10:11], v[2:3], v[8:9], v[6:7]
	v_pk_fma_f32 v[8:9], v[0:1], v[16:17], v[4:5]
	s_cbranch_vccnz .LBB0_702
	v_lshl_add_u64 v[16:17], v[134:135], 2, v[140:141]
	global_store_dwordx4 v[16:17], v[8:11], off offset:576
	s_cbranch_execnz .LBB0_657

; __device__ __forceinline__ unsigned cvt_pk_bf16(float lo, float hi) { unsigned r; asm volatile("v_cvt_pk_bf16_f32 %0, %1, %2" : "=v"(r) : "v"(lo), "v"(hi)); return r; }
;     __device__ __forceinline__ void fused(f32x4 (&acc)[2][2][4][2], const Unit& u, int wr, int wc, int fr, int fq, LAS unsigned char* lds) const {
;     ...
; #pragma unroll
;         for (int bj = 0; bj < 2; ++bj)
; #pragma unroll
;             for (int n = 0; n < 2; ++n) { const int cc = col0 + bj * HALF + n * 16; const f32x4 g4 = *(const f32x4*)(g + cc), b4 = *(const f32x4*)(b + cc);
; #pragma unroll
;                 for (int ai = 0; ai < 2; ++ai)
; #pragma unroll
;                     for (int m = 0; m < 4; ++m) { const int rl = rl0 + ai * HALF + m * 16; const float mean = S2[rl * 2], rstd = S2[rl * 2 + 1];
;                         const f32x4 y = (acc[ai][bj][m][n] - mean) * rstd * g4 + b4; const size_t row = (size_t)(u.pm * BM + rl);
;                         if (of) *(f32x4*)(of + row * DM + cc) = y;
;                         else { u32x2 pk; pk.x = cvt_pk_bf16(y[0], y[1]); pk.y = cvt_pk_bf16(y[2], y[3]); *(u32x2*)(ob + row * LDX + cc) = pk; } }
;                 asm volatile("" ::: "memory"); }
.LBB0_657:
	s_and_b64 vcc, exec, s[0:1]
	s_waitcnt lgkmcnt(0)
	v_sub_f32_e32 v11, v91, v212
	v_sub_f32_e32 v10, v90, v212
	v_sub_f32_e32 v17, v85, v212
	v_sub_f32_e32 v16, v84, v212
	v_pk_mul_f32 v[16:17], v[16:17], v[212:213] op_sel:[0,1]
	v_pk_mul_f32 v[8:9], v[10:11], v[212:213] op_sel:[0,1]
	s_nop 0
	v_pk_fma_f32 v[10:11], v[2:3], v[8:9], v[6:7]
	v_pk_fma_f32 v[8:9], v[0:1], v[16:17], v[4:5]
	s_cbranch_vccnz .LBB0_703
	v_lshl_add_u64 v[16:17], v[134:135], 2, v[142:143]
	global_store_dwordx4 v[16:17], v[8:11], off offset:576
	s_cbranch_execnz .LBB0_660

; __device__ __forceinline__ unsigned cvt_pk_bf16(float lo, float hi) { unsigned r; asm volatile("v_cvt_pk_bf16_f32 %0, %1, %2" : "=v"(r) : "v"(lo), "v"(hi)); return r; }
;     __device__ __forceinline__ void fused(f32x4 (&acc)[2][2][4][2], const Unit& u, int wr, int wc, int fr, int fq, LAS unsigned char* lds) const {
;     ...
; #pragma unroll
;         for (int bj = 0; bj < 2; ++bj)
; #pragma unroll
;             for (int n = 0; n < 2; ++n) { const int cc = col0 + bj * HALF + n * 16; const f32x4 g4 = *(const f32x4*)(g + cc), b4 = *(const f32x4*)(b + cc);
; #pragma unroll
;                 for (int ai = 0; ai < 2; ++ai)
; #pragma unroll
;                     for (int m = 0; m < 4; ++m) { const int rl = rl0 + ai * HALF + m * 16; const float mean = S2[rl * 2], rstd = S2[rl * 2 + 1];
;                         const f32x4 y = (acc[ai][bj][m][n] - mean) * rstd * g4 + b4; const size_t row = (size_t)(u.pm * BM + rl);
;                         if (of) *(f32x4*)(of + row * DM + cc) = y;
;                         else { u32x2 pk; pk.x = cvt_pk_bf16(y[0], y[1]); pk.y = cvt_pk_bf16(y[2], y[3]); *(u32x2*)(ob + row * LDX + cc) = pk; } }
;                 asm volatile("" ::: "memory"); }
.LBB0_660:
	s_and_b64 vcc, exec, s[0:1]
	s_waitcnt lgkmcnt(0)
	v_sub_f32_e32 v11, v75, v214
	v_sub_f32_e32 v10, v74, v214
	v_sub_f32_e32 v17, v69, v214
	v_sub_f32_e32 v16, v68, v214
	v_pk_mul_f32 v[16:17], v[16:17], v[214:215] op_sel:[0,1]
	v_pk_mul_f32 v[8:9], v[10:11], v[214:215] op_sel:[0,1]
	s_nop 0
	v_pk_fma_f32 v[10:11], v[2:3], v[8:9], v[6:7]
	v_pk_fma_f32 v[8:9], v[0:1], v[16:17], v[4:5]
	s_cbranch_vccnz .LBB0_704
	v_lshl_add_u64 v[16:17], v[134:135], 2, v[144:145]
	global_store_dwordx4 v[16:17], v[8:11], off offset:576
	s_cbranch_execnz .LBB0_663

; __device__ __forceinline__ unsigned cvt_pk_bf16(float lo, float hi) { unsigned r; asm volatile("v_cvt_pk_bf16_f32 %0, %1, %2" : "=v"(r) : "v"(lo), "v"(hi)); return r; }
;     __device__ __forceinline__ void fused(f32x4 (&acc)[2][2][4][2], const Unit& u, int wr, int wc, int fr, int fq, LAS unsigned char* lds) const {
;     ...
; #pragma unroll
;         for (int bj = 0; bj < 2; ++bj)
; #pragma unroll
;             for (int n = 0; n < 2; ++n) { const int cc = col0 + bj * HALF + n * 16; const f32x4 g4 = *(const f32x4*)(g + cc), b4 = *(const f32x4*)(b + cc);
; #pragma unroll
;                 for (int ai = 0; ai < 2; ++ai)
; #pragma unroll
;                     for (int m = 0; m < 4; ++m) { const int rl = rl0 + ai * HALF + m * 16; const float mean = S2[rl * 2], rstd = S2[rl * 2 + 1];
;                         const f32x4 y = (acc[ai][bj][m][n] - mean) * rstd * g4 + b4; const size_t row = (size_t)(u.pm * BM + rl);
;                         if (of) *(f32x4*)(of + row * DM + cc) = y;
;                         else { u32x2 pk; pk.x = cvt_pk_bf16(y[0], y[1]); pk.y = cvt_pk_bf16(y[2], y[3]); *(u32x2*)(ob + row * LDX + cc) = pk; } }
;                 asm volatile("" ::: "memory"); }
.LBB0_663:
	s_and_b64 vcc, exec, s[0:1]
	s_waitcnt lgkmcnt(0)
	v_sub_f32_e32 v11, v57, v246
	v_sub_f32_e32 v10, v56, v246
	v_sub_f32_e32 v17, v51, v246
	v_sub_f32_e32 v16, v50, v246
	v_pk_mul_f32 v[16:17], v[16:17], v[246:247] op_sel:[0,1]
	v_pk_mul_f32 v[8:9], v[10:11], v[246:247] op_sel:[0,1]
	s_nop 0
	v_pk_fma_f32 v[10:11], v[2:3], v[8:9], v[6:7]
	v_pk_fma_f32 v[8:9], v[0:1], v[16:17], v[4:5]
	s_cbranch_vccnz .LBB0_705
	v_lshl_add_u64 v[16:17], v[134:135], 2, v[148:149]
	global_store_dwordx4 v[16:17], v[8:11], off offset:576
	s_cbranch_execnz .LBB0_666

; __device__ __forceinline__ unsigned cvt_pk_bf16(float lo, float hi) { unsigned r; asm volatile("v_cvt_pk_bf16_f32 %0, %1, %2" : "=v"(r) : "v"(lo), "v"(hi)); return r; }
;     __device__ __forceinline__ void fused(f32x4 (&acc)[2][2][4][2], const Unit& u, int wr, int wc, int fr, int fq, LAS unsigned char* lds) const {
;     ...
; #pragma unroll
;         for (int bj = 0; bj < 2; ++bj)
; #pragma unroll
;             for (int n = 0; n < 2; ++n) { const int cc = col0 + bj * HALF + n * 16; const f32x4 g4 = *(const f32x4*)(g + cc), b4 = *(const f32x4*)(b + cc);
; #pragma unroll
;                 for (int ai = 0; ai < 2; ++ai)
; #pragma unroll
;                     for (int m = 0; m < 4; ++m) { const int rl = rl0 + ai * HALF + m * 16; const float mean = S2[rl * 2], rstd = S2[rl * 2 + 1];
;                         const f32x4 y = (acc[ai][bj][m][n] - mean) * rstd * g4 + b4; const size_t row = (size_t)(u.pm * BM + rl);
;                         if (of) *(f32x4*)(of + row * DM + cc) = y;
;                         else { u32x2 pk; pk.x = cvt_pk_bf16(y[0], y[1]); pk.y = cvt_pk_bf16(y[2], y[3]); *(u32x2*)(ob + row * LDX + cc) = pk; } }
;                 asm volatile("" ::: "memory"); }
.LBB0_666:
	s_and_b64 vcc, exec, s[0:1]
	s_waitcnt lgkmcnt(0)
	v_sub_f32_e32 v11, v41, v181
	v_sub_f32_e32 v10, v40, v181
	v_sub_f32_e32 v17, v35, v181
	v_sub_f32_e32 v16, v34, v181
	v_pk_mul_f32 v[16:17], v[16:17], v[160:161] op_sel:[0,1]
	v_pk_mul_f32 v[8:9], v[10:11], v[160:161] op_sel:[0,1]
	s_nop 0
	v_pk_fma_f32 v[10:11], v[2:3], v[8:9], v[6:7]
	v_pk_fma_f32 v[8:9], v[0:1], v[16:17], v[4:5]
	s_cbranch_vccnz .LBB0_706
	v_lshl_add_u64 v[16:17], v[134:135], 2, v[152:153]
	global_store_dwordx4 v[16:17], v[8:11], off offset:576
	s_cbranch_execnz .LBB0_669

; __device__ __forceinline__ unsigned cvt_pk_bf16(float lo, float hi) { unsigned r; asm volatile("v_cvt_pk_bf16_f32 %0, %1, %2" : "=v"(r) : "v"(lo), "v"(hi)); return r; }
;     __device__ __forceinline__ void fused(f32x4 (&acc)[2][2][4][2], const Unit& u, int wr, int wc, int fr, int fq, LAS unsigned char* lds) const {
;     ...
; #pragma unroll
;         for (int bj = 0; bj < 2; ++bj)
; #pragma unroll
;             for (int n = 0; n < 2; ++n) { const int cc = col0 + bj * HALF + n * 16; const f32x4 g4 = *(const f32x4*)(g + cc), b4 = *(const f32x4*)(b + cc);
; #pragma unroll
;                 for (int ai = 0; ai < 2; ++ai)
; #pragma unroll
;                     for (int m = 0; m < 4; ++m) { const int rl = rl0 + ai * HALF + m * 16; const float mean = S2[rl * 2], rstd = S2[rl * 2 + 1];
;                         const f32x4 y = (acc[ai][bj][m][n] - mean) * rstd * g4 + b4; const size_t row = (size_t)(u.pm * BM + rl);
;                         if (of) *(f32x4*)(of + row * DM + cc) = y;
;                         else { u32x2 pk; pk.x = cvt_pk_bf16(y[0], y[1]); pk.y = cvt_pk_bf16(y[2], y[3]); *(u32x2*)(ob + row * LDX + cc) = pk; } }
;                 asm volatile("" ::: "memory"); }
.LBB0_669:
	s_and_b64 vcc, exec, s[0:1]
	s_waitcnt lgkmcnt(0)
	v_sub_f32_e32 v11, v25, v183
	v_sub_f32_e32 v10, v24, v183
	v_sub_f32_e32 v17, v19, v183
	v_sub_f32_e32 v16, v18, v183
	v_pk_mul_f32 v[16:17], v[16:17], v[166:167] op_sel:[0,1]
	v_pk_mul_f32 v[8:9], v[10:11], v[166:167] op_sel:[0,1]
	s_nop 0
	v_pk_fma_f32 v[10:11], v[2:3], v[8:9], v[6:7]
	v_pk_fma_f32 v[8:9], v[0:1], v[16:17], v[4:5]
	s_cbranch_vccnz .LBB0_707
	v_lshl_add_u64 v[16:17], v[134:135], 2, v[154:155]
	global_store_dwordx4 v[16:17], v[8:11], off offset:576
	s_cbranch_execnz .LBB0_672

; __device__ __forceinline__ unsigned cvt_pk_bf16(float lo, float hi) { unsigned r; asm volatile("v_cvt_pk_bf16_f32 %0, %1, %2" : "=v"(r) : "v"(lo), "v"(hi)); return r; }
;     __device__ __forceinline__ void fused(f32x4 (&acc)[2][2][4][2], const Unit& u, int wr, int wc, int fr, int fq, LAS unsigned char* lds) const {
;     ...
; #pragma unroll
;         for (int bj = 0; bj < 2; ++bj)
; #pragma unroll
;             for (int n = 0; n < 2; ++n) { const int cc = col0 + bj * HALF + n * 16; const f32x4 g4 = *(const f32x4*)(g + cc), b4 = *(const f32x4*)(b + cc);
; #pragma unroll
;                 for (int ai = 0; ai < 2; ++ai)
; #pragma unroll
;                     for (int m = 0; m < 4; ++m) { const int rl = rl0 + ai * HALF + m * 16; const float mean = S2[rl * 2], rstd = S2[rl * 2 + 1];
;                         const f32x4 y = (acc[ai][bj][m][n] - mean) * rstd * g4 + b4; const size_t row = (size_t)(u.pm * BM + rl);
;                         if (of) *(f32x4*)(of + row * DM + cc) = y;
;                         else { u32x2 pk; pk.x = cvt_pk_bf16(y[0], y[1]); pk.y = cvt_pk_bf16(y[2], y[3]); *(u32x2*)(ob + row * LDX + cc) = pk; } }
;                 asm volatile("" ::: "memory"); }
.LBB0_672:
	s_and_b64 vcc, exec, s[0:1]
	s_waitcnt lgkmcnt(0)
	v_sub_f32_e32 v11, v15, v64
	v_sub_f32_e32 v10, v14, v64
	v_sub_f32_e32 v13, v13, v64
	v_sub_f32_e32 v12, v12, v64
	v_pk_mul_f32 v[12:13], v[12:13], v[168:169] op_sel:[0,1]
	v_pk_mul_f32 v[8:9], v[10:11], v[168:169] op_sel:[0,1]
	v_pk_fma_f32 v[0:1], v[0:1], v[12:13], v[4:5]
	v_pk_fma_f32 v[2:3], v[2:3], v[8:9], v[6:7]
	s_cbranch_vccnz .LBB0_708
	v_lshl_add_u64 v[4:5], v[134:135], 2, v[156:157]
	global_store_dwordx4 v[4:5], v[0:3], off offset:576
	s_cbranch_execnz .LBB0_675
